# P1->P2-idle conversion split at item 0x6000 (was 0x5000)
# speedup vs baseline: 1.0081x; 1.0007x over previous
.LBB0_89:
	v_lshlrev_b32_e32 v1, 2, v0
	s_cmpk_eq_i32 s92, 0x100
	s_movk_i32 s0, 0x6000
	v_and_b32_e32 v68, 28, v1
	s_cselect_b32 s4, s0, 0xa100
	s_ashr_i32 s30, s94, 31
	s_ashr_i32 s31, s92, 31
	v_and_b32_e32 v66, 56, v0
	v_mov_b32_e32 v71, 0
	v_lshlrev_b32_e32 v70, 2, v68
	s_cmp_lg_u64 s[20:21], 0
	s_waitcnt lgkmcnt(0)
	v_lshl_add_u64 v[72:73], s[50:51], 0, v[70:71]
	v_lshlrev_b32_e32 v70, 1, v66
	s_mov_b32 s5, 0
	s_cselect_b64 s[2:3], -1, 0
	s_add_u32 s33, s84, 0x25400000
	v_lshl_add_u64 v[2:3], s[84:85], 0, v[70:71]
	s_mov_b64 s[6:7], 0x1000000
	v_cmp_eq_u32_e64 s[0:1], 0, v154
	s_addc_u32 s34, s85, 0
	v_lshl_add_u64 v[74:75], v[2:3], 0, s[6:7]
	s_add_i32 s35, 0, 0x20190
	v_mov_b64_e32 v[76:77], s[4:5]
	s_movk_i32 s36, 0x2b00
	s_movk_i32 s37, 0x5000
	s_mov_b32 s38, 0xa000
	s_mov_b32 s39, 0x10000
	s_mov_b32 s40, 0xac000
	s_mov_b32 s41, 0xb1000
	s_mov_b32 s42, 0xb6000
	s_mov_b64 s[4:5], 0xbc200
	s_mov_b32 s43, 0x15800
	s_movk_i32 s44, 0x1000
	s_mov_b64 s[6:7], 0x80
	s_mov_b32 s45, 0x11000
	s_mov_b64 s[12:13], 0x11800
	v_lshlrev_b32_e32 v70, 2, v68
	v_lshlrev_b32_e32 v78, 1, v66
	s_branch .LBB0_92

.LBB0_251:
	s_cmpk_lg_i32 s92, 0x100
	s_cselect_b64 s[0:1], -1, 0
	s_cmpk_lt_i32 s87, 0x80
	s_cselect_b64 s[2:3], -1, 0
	s_or_b64 s[0:1], s[2:3], s[0:1]
	s_and_b64 vcc, exec, s[0:1]
	s_cbranch_vccnz .LBB0_262
	s_mov_b32 s3, 0
	v_cmp_eq_u32_e32 vcc, 0, v0
	s_waitcnt lgkmcnt(0)
	s_barrier
	s_and_saveexec_b64 s[0:1], vcc
	s_add_i32 s2, 0, 0x20190
	v_mov_b32_e32 v2, 0
	v_mov_b32_e32 v3, s2
	ds_write_b32 v3, v2
	s_or_b64 exec, exec, s[0:1]
	v_and_b32_e32 v1, 28, v1
	v_readlane_b32 s24, v240, 2
	v_and_b32_e32 v10, 56, v0
	v_lshlrev_b32_e32 v2, 2, v1
	v_mov_b32_e32 v3, 0
	v_readlane_b32 s30, v240, 8
	v_readlane_b32 s31, v240, 9
	v_readlane_b32 s25, v240, 3
	s_mov_b64 s[6:7], 0x1a800000
	v_lshl_add_u64 v[4:5], s[30:31], 0, v[2:3]
	v_lshlrev_b32_e32 v2, 1, v10
	v_lshl_add_u64 v[6:7], s[84:85], 0, v[2:3]
	s_add_i32 s12, s87, 0x7580
	v_cmp_eq_u32_e64 s[0:1], 0, v154
	v_lshl_add_u64 v[6:7], v[6:7], 0, s[6:7]
	s_add_i32 s13, 0, 0x20190
	v_mov_b64_e32 v[8:9], 0xa0ff
	s_movk_i32 s14, 0x5000
	s_mov_b32 s15, 0xa000
	s_mov_b32 s22, 0x10000
	s_mov_b32 s23, 0xac000
	s_mov_b32 s24, 0xb1000
	s_mov_b32 s25, 0xb6000
	s_waitcnt lgkmcnt(0)
	s_barrier
	v_readlane_b32 s26, v240, 4
	v_readlane_b32 s27, v240, 5
	v_readlane_b32 s28, v240, 6
	v_readlane_b32 s29, v240, 7
	v_writelane_b32 v254, s4, 0
	v_writelane_b32 v254, s5, 1
	v_writelane_b32 v254, s33, 2
	v_writelane_b32 v254, s34, 3
	v_writelane_b32 v254, s35, 4
	v_writelane_b32 v254, s36, 5
	v_writelane_b32 v254, s37, 6
	v_writelane_b32 v254, s38, 7
	v_writelane_b32 v254, s39, 8
	v_writelane_b32 v254, s40, 9
	v_writelane_b32 v254, s41, 10
	v_writelane_b32 v254, s42, 11
	v_writelane_b32 v254, s43, 12
	v_writelane_b32 v254, s44, 13
	v_writelane_b32 v254, s45, 14
	v_writelane_b32 v254, s46, 15
	v_writelane_b32 v254, s47, 16
	v_writelane_b32 v254, s48, 17
	v_writelane_b32 v254, s49, 18
	v_writelane_b32 v254, s52, 19
	v_writelane_b32 v254, s53, 20
	v_writelane_b32 v254, s54, 21
	v_writelane_b32 v254, s55, 22
	v_writelane_b32 v254, s56, 23
	v_writelane_b32 v254, s57, 24
	v_writelane_b32 v254, s58, 25
	v_writelane_b32 v254, s59, 26
	v_writelane_b32 v254, s92, 27
	v_writelane_b32 v254, s94, 28
	s_movk_i32 s92, 0x80
	s_add_i32 s94, s87, 0x5f80
	s_mov_b32 s101, 3
	s_branch .LBB0_89
